# P1: the two wave halves no longer align their epilogues (leading half's epilogue overlaps the trailing half's last MFMA block; barrier parity kept via one extra barrier on the last tile)
# speedup vs baseline: 1.0029x; 1.0029x over previous
; #define PG8_STAGE(bufoff, gbase, voff) do { _Pragma("unroll") for (int _i = 0; _i < 2; ++_i) \
;         __builtin_amdgcn_global_load_lds((const unsigned*)((const char*)(gbase) + (voff)[_i]), (PG8_LAS unsigned*)(lds + (bufoff) + ldsw + _i * 8192), 16, 0, 0); } while (0)
; #define PG8_LDA(dst, b, h) do { _Pragma("unroll") for (int m = 0; m < 4; ++m) _Pragma("unroll") for (int k = 0; k < 2; ++k) dst[m][k] = *(const PG8_LAS bf16x8*)(lds + PG8_SA(b, h) + aoff + m * 2048 + k * 1024); } while (0)
; #define PG8_LDB(dst, b, h) do { _Pragma("unroll") for (int n = 0; n < 2; ++n) _Pragma("unroll") for (int k = 0; k < 2; ++k) dst[n][k] = *(const PG8_LAS bf16x8*)(lds + PG8_SB(b, h) + boff + n * 2048 + k * 1024); } while (0)
; #define PG8_MMA(ai, bj, At, Bt) do { __builtin_amdgcn_s_setprio(1); _Pragma("unroll") for (int m = 0; m < 4; ++m) _Pragma("unroll") for (int n = 0; n < 2; ++n) _Pragma("unroll") for (int k = 0; k < 2; ++k) \
;         acc[ai][bj][m][n] = __builtin_amdgcn_mfma_f32_16x16x32_bf16(Bt[n][k], At[m][k], acc[ai][bj][m][n], 0, 0, 0); __builtin_amdgcn_s_setprio(0); } while (0)
; #define PG8_WAIT_V(n) asm volatile("s_waitcnt vmcnt(" #n ")" ::: "memory")
; #define PG8_WAIT_L(n) asm volatile("s_waitcnt lgkmcnt(" #n ")" ::: "memory")
; #define PG8_BAR __builtin_amdgcn_s_barrier()
; #define PG8_SCHED __builtin_amdgcn_sched_barrier(0)
; template <class Epi, class Sched, bool ALIGN_EPI = false, bool SP2 = false, bool RS = false, bool BPRE = false>
; __device__ __forceinline__ void gemm_phase(PG8_LAS unsigned char* lds, const Gemm g, const Sched& S, const Epi& E, const float* rs_ss = nullptr, PG8_LAS float* rs_tab = nullptr) {
;     ...
;             PG8_LDB(B0, 0, 0); PG8_LDB(B1, 0, 1); PG8_SCHED; PG8_LDA(At, 0, 0); PG8_STAGE(PG8_SA(1, 1), a1 + hstep, voffA);
;             PG8_WAIT_V(8); PG8_WAIT_L(0); PG8_BAR; PG8_MMA(0, 0, At, B0); PG8_MMA(0, 1, At, B1); PG8_BAR; PG8_SCHED;
;             PG8_LDA(At, 0, 1); PG8_STAGE(PG8_SB(0, 0), b2, voffB); PG8_STAGE(PG8_SB(0, 1), b2 + hstep, voffB); PG8_STAGE(PG8_SA(0, 0), a2, voffA);
;             PG8_WAIT_V(8); PG8_WAIT_L(0); PG8_BAR; PG8_MMA(1, 0, At, B0); PG8_MMA(1, 1, At, B1); PG8_BAR; PG8_SCHED;
.LBB0_196:
	ds_read_b128 v[130:133], v161
	ds_read_b128 v[134:137], v161 offset:1024
	ds_read_b128 v[152:155], v161 offset:2048
	ds_read_b128 v[156:159], v161 offset:3072
	ds_read_b128 v[166:169], v162
	ds_read_b128 v[170:173], v162 offset:1024
	ds_read_b128 v[174:177], v162 offset:2048
	ds_read_b128 v[182:185], v162 offset:3072
	s_add_u32 s58, s56, 0xfff84000
	s_addc_u32 s59, s57, -1
	s_cmp_eq_u32 s89, 28
	s_cselect_b32 s70, s19, s58
	s_cselect_b32 s71, s5, s59
	s_cselect_b32 s60, s47, s87
	s_cselect_b32 s61, s17, s88
	s_add_u32 s58, s70, 0x4000
	s_addc_u32 s59, s71, 0
	v_lshl_add_u64 v[178:179], s[56:57], 0, v[138:139]
	s_add_i32 m0, s72, 0xc000
	ds_read_b128 v[186:189], v163
	ds_read_b128 v[190:193], v163 offset:1024
	ds_read_b128 v[194:197], v163 offset:2048
	ds_read_b128 v[198:201], v163 offset:3072
	ds_read_b128 v[202:205], v163 offset:4096
	ds_read_b128 v[206:209], v163 offset:5120
	ds_read_b128 v[210:213], v163 offset:6144
	ds_read_b128 v[214:217], v163 offset:7168
	global_load_lds_dwordx4 v[178:179], off
	v_lshl_add_u64 v[178:179], s[56:57], 0, v[146:147]
	s_add_i32 m0, s72, 0xe000
	s_nop 0
	global_load_lds_dwordx4 v[178:179], off
	s_waitcnt vmcnt(8)
	s_waitcnt lgkmcnt(0)
	s_barrier
	s_setprio 1
	s_waitcnt lgkmcnt(0)
	v_mfma_f32_16x16x32_bf16 v[126:129], v[130:133], v[186:189], v[126:129]
	v_mfma_f32_16x16x32_bf16 v[122:125], v[152:155], v[186:189], v[122:125]
	v_mfma_f32_16x16x32_bf16 v[110:113], v[130:133], v[194:197], v[110:113]
	v_mfma_f32_16x16x32_bf16 v[106:109], v[152:155], v[194:197], v[106:109]
	v_mfma_f32_16x16x32_bf16 v[94:97], v[130:133], v[202:205], v[94:97]
	v_mfma_f32_16x16x32_bf16 v[90:93], v[152:155], v[202:205], v[90:93]
	v_mfma_f32_16x16x32_bf16 v[78:81], v[130:133], v[210:213], v[78:81]
	v_mfma_f32_16x16x32_bf16 v[74:77], v[152:155], v[210:213], v[74:77]
	v_mfma_f32_16x16x32_bf16 v[126:129], v[134:137], v[190:193], v[126:129]
	v_mfma_f32_16x16x32_bf16 v[122:125], v[156:159], v[190:193], v[122:125]
	v_mfma_f32_16x16x32_bf16 v[110:113], v[134:137], v[198:201], v[110:113]
	v_mfma_f32_16x16x32_bf16 v[106:109], v[156:159], v[198:201], v[106:109]
	v_mfma_f32_16x16x32_bf16 v[94:97], v[134:137], v[206:209], v[94:97]
	v_mfma_f32_16x16x32_bf16 v[90:93], v[156:159], v[206:209], v[90:93]
	v_mfma_f32_16x16x32_bf16 v[78:81], v[134:137], v[214:217], v[78:81]
	v_mfma_f32_16x16x32_bf16 v[74:77], v[156:159], v[214:217], v[74:77]
	s_setprio 0
	s_setprio 1
	v_mfma_f32_16x16x32_bf16 v[118:121], v[166:169], v[186:189], v[118:121]
	v_mfma_f32_16x16x32_bf16 v[114:117], v[174:177], v[186:189], v[114:117]
	v_mfma_f32_16x16x32_bf16 v[102:105], v[166:169], v[194:197], v[102:105]
	v_mfma_f32_16x16x32_bf16 v[98:101], v[174:177], v[194:197], v[98:101]
	v_mfma_f32_16x16x32_bf16 v[86:89], v[166:169], v[202:205], v[86:89]
	v_mfma_f32_16x16x32_bf16 v[82:85], v[174:177], v[202:205], v[82:85]
	v_mfma_f32_16x16x32_bf16 v[70:73], v[166:169], v[210:213], v[70:73]
	v_mfma_f32_16x16x32_bf16 v[66:69], v[174:177], v[210:213], v[66:69]
	v_mfma_f32_16x16x32_bf16 v[118:121], v[170:173], v[190:193], v[118:121]
	v_mfma_f32_16x16x32_bf16 v[114:117], v[182:185], v[190:193], v[114:117]
	v_mfma_f32_16x16x32_bf16 v[102:105], v[170:173], v[198:201], v[102:105]
	v_mfma_f32_16x16x32_bf16 v[98:101], v[182:185], v[198:201], v[98:101]
	v_mfma_f32_16x16x32_bf16 v[86:89], v[170:173], v[206:209], v[86:89]
	v_mfma_f32_16x16x32_bf16 v[82:85], v[182:185], v[206:209], v[82:85]
	v_mfma_f32_16x16x32_bf16 v[70:73], v[170:173], v[214:217], v[70:73]
	v_mfma_f32_16x16x32_bf16 v[66:69], v[182:185], v[214:217], v[66:69]
	s_setprio 0
	s_barrier
	s_add_i32 s90, s83, s15
	v_lshl_add_u64 v[178:179], s[60:61], 0, v[138:139]
	s_mov_b32 m0, s90
	ds_read_b128 v[186:189], v163 offset:16384
	ds_read_b128 v[190:193], v163 offset:17408
	ds_read_b128 v[194:197], v163 offset:18432
	ds_read_b128 v[198:201], v163 offset:19456
	ds_read_b128 v[202:205], v163 offset:20480
	ds_read_b128 v[206:209], v163 offset:21504
	ds_read_b128 v[210:213], v163 offset:22528
	ds_read_b128 v[214:217], v163 offset:23552
	global_load_lds_dwordx4 v[178:179], off
	s_add_i32 m0, s90, 0x2000
	s_add_u32 s90, s60, 0x80000
	v_lshl_add_u64 v[178:179], s[60:61], 0, v[140:141]
	s_addc_u32 s91, s61, 0
	s_add_i32 s92, s86, s15
	global_load_lds_dwordx4 v[178:179], off
	v_lshl_add_u64 v[178:179], s[90:91], 0, v[138:139]
	s_mov_b32 m0, s92
	s_nop 0
	global_load_lds_dwordx4 v[178:179], off
	v_lshl_add_u64 v[178:179], s[90:91], 0, v[140:141]
	s_add_i32 m0, s92, 0x2000
	s_nop 0
	global_load_lds_dwordx4 v[178:179], off
	v_lshl_add_u64 v[178:179], s[70:71], 0, v[138:139]
	s_mov_b32 m0, s72
	s_nop 0
	global_load_lds_dwordx4 v[178:179], off
	v_lshl_add_u64 v[178:179], s[70:71], 0, v[140:141]
	s_mov_b32 m0, s73
	s_nop 0
	global_load_lds_dwordx4 v[178:179], off
	s_waitcnt vmcnt(8)
	s_waitcnt lgkmcnt(0)
	s_barrier
; #define PG8_STAGE(bufoff, gbase, voff) do { _Pragma("unroll") for (int _i = 0; _i < 2; ++_i) \
;         __builtin_amdgcn_global_load_lds((const unsigned*)((const char*)(gbase) + (voff)[_i]), (PG8_LAS unsigned*)(lds + (bufoff) + ldsw + _i * 8192), 16, 0, 0); } while (0)
; #define PG8_LDA(dst, b, h) do { _Pragma("unroll") for (int m = 0; m < 4; ++m) _Pragma("unroll") for (int k = 0; k < 2; ++k) dst[m][k] = *(const PG8_LAS bf16x8*)(lds + PG8_SA(b, h) + aoff + m * 2048 + k * 1024); } while (0)
; #define PG8_LDB(dst, b, h) do { _Pragma("unroll") for (int n = 0; n < 2; ++n) _Pragma("unroll") for (int k = 0; k < 2; ++k) dst[n][k] = *(const PG8_LAS bf16x8*)(lds + PG8_SB(b, h) + boff + n * 2048 + k * 1024); } while (0)
; #define PG8_MMA(ai, bj, At, Bt) do { __builtin_amdgcn_s_setprio(1); _Pragma("unroll") for (int m = 0; m < 4; ++m) _Pragma("unroll") for (int n = 0; n < 2; ++n) _Pragma("unroll") for (int k = 0; k < 2; ++k) \
;         acc[ai][bj][m][n] = __builtin_amdgcn_mfma_f32_16x16x32_bf16(Bt[n][k], At[m][k], acc[ai][bj][m][n], 0, 0, 0); __builtin_amdgcn_s_setprio(0); } while (0)
; #define PG8_WAIT_V(n) asm volatile("s_waitcnt vmcnt(" #n ")" ::: "memory")
; #define PG8_WAIT_L(n) asm volatile("s_waitcnt lgkmcnt(" #n ")" ::: "memory")
; #define PG8_BAR __builtin_amdgcn_s_barrier()
; #define PG8_SCHED __builtin_amdgcn_sched_barrier(0)
; template <class Epi, class Sched, bool ALIGN_EPI = false, bool SP2 = false, bool RS = false, bool BPRE = false>
; __device__ __forceinline__ void gemm_phase(PG8_LAS unsigned char* lds, const Gemm g, const Sched& S, const Epi& E, const float* rs_ss = nullptr, PG8_LAS float* rs_tab = nullptr) {
;     ...
;             PG8_WAIT_V(8); PG8_WAIT_L(0); PG8_BAR; PG8_MMA(1, 0, At, B0); PG8_MMA(1, 1, At, B1); PG8_BAR; PG8_SCHED;
;             PG8_LDB(B0, 1, 0); PG8_LDB(B1, 1, 1); PG8_SCHED; PG8_LDA(At, 1, 0); PG8_STAGE(PG8_SA(0, 1), a2 + hstep, voffA);
;             PG8_WAIT_V(8); PG8_WAIT_L(0); PG8_BAR; PG8_MMA(0, 0, At, B0); PG8_MMA(0, 1, At, B1); PG8_BAR; PG8_SCHED;
	s_setprio 1
	s_waitcnt lgkmcnt(0)
	v_mfma_f32_16x16x32_bf16 v[62:65], v[130:133], v[186:189], v[62:65]
	v_mfma_f32_16x16x32_bf16 v[58:61], v[152:155], v[186:189], v[58:61]
	v_mfma_f32_16x16x32_bf16 v[46:49], v[130:133], v[194:197], v[46:49]
	v_mfma_f32_16x16x32_bf16 v[42:45], v[152:155], v[194:197], v[42:45]
	v_mfma_f32_16x16x32_bf16 v[30:33], v[130:133], v[202:205], v[30:33]
	v_mfma_f32_16x16x32_bf16 v[26:29], v[152:155], v[202:205], v[26:29]
	v_mfma_f32_16x16x32_bf16 v[14:17], v[130:133], v[210:213], v[14:17]
	v_mfma_f32_16x16x32_bf16 v[10:13], v[152:155], v[210:213], v[10:13]
	v_mfma_f32_16x16x32_bf16 v[62:65], v[134:137], v[190:193], v[62:65]
	v_mfma_f32_16x16x32_bf16 v[58:61], v[156:159], v[190:193], v[58:61]
	v_mfma_f32_16x16x32_bf16 v[46:49], v[134:137], v[198:201], v[46:49]
	v_mfma_f32_16x16x32_bf16 v[42:45], v[156:159], v[198:201], v[42:45]
	v_mfma_f32_16x16x32_bf16 v[30:33], v[134:137], v[206:209], v[30:33]
	v_mfma_f32_16x16x32_bf16 v[26:29], v[156:159], v[206:209], v[26:29]
	v_mfma_f32_16x16x32_bf16 v[14:17], v[134:137], v[214:217], v[14:17]
	v_mfma_f32_16x16x32_bf16 v[10:13], v[156:159], v[214:217], v[10:13]
	s_setprio 0
	s_setprio 1
	v_mfma_f32_16x16x32_bf16 v[54:57], v[166:169], v[186:189], v[54:57]
	v_mfma_f32_16x16x32_bf16 v[50:53], v[174:177], v[186:189], v[50:53]
	v_mfma_f32_16x16x32_bf16 v[38:41], v[166:169], v[194:197], v[38:41]
	v_mfma_f32_16x16x32_bf16 v[34:37], v[174:177], v[194:197], v[34:37]
	v_mfma_f32_16x16x32_bf16 v[22:25], v[166:169], v[202:205], v[22:25]
	v_mfma_f32_16x16x32_bf16 v[18:21], v[174:177], v[202:205], v[18:21]
	v_mfma_f32_16x16x32_bf16 v[6:9], v[166:169], v[210:213], v[6:9]
	v_mfma_f32_16x16x32_bf16 v[2:5], v[174:177], v[210:213], v[2:5]
	v_mfma_f32_16x16x32_bf16 v[54:57], v[170:173], v[190:193], v[54:57]
	v_mfma_f32_16x16x32_bf16 v[50:53], v[182:185], v[190:193], v[50:53]
	v_mfma_f32_16x16x32_bf16 v[38:41], v[170:173], v[198:201], v[38:41]
	v_mfma_f32_16x16x32_bf16 v[34:37], v[182:185], v[198:201], v[34:37]
	v_mfma_f32_16x16x32_bf16 v[22:25], v[170:173], v[206:209], v[22:25]
	v_mfma_f32_16x16x32_bf16 v[18:21], v[182:185], v[206:209], v[18:21]
	v_mfma_f32_16x16x32_bf16 v[6:9], v[170:173], v[214:217], v[6:9]
	v_mfma_f32_16x16x32_bf16 v[2:5], v[182:185], v[214:217], v[2:5]
	s_setprio 0
	s_barrier
	s_add_i32 s90, 0, 0x18000
	v_add_u32_e32 v143, s90, v160
	s_add_i32 s91, 0, 0x1c000
	ds_read_b128 v[130:133], v143
	ds_read_b128 v[134:137], v143 offset:1024
	ds_read_b128 v[152:155], v143 offset:2048
	ds_read_b128 v[156:159], v143 offset:3072
	v_add_u32_e32 v143, s91, v160
	ds_read_b128 v[166:169], v143
	ds_read_b128 v[170:173], v143 offset:1024
	ds_read_b128 v[174:177], v143 offset:2048
	ds_read_b128 v[182:185], v143 offset:3072
	s_add_u32 s70, s70, 0x80000
	s_addc_u32 s71, s71, 0
	s_mov_b32 m0, s74
	v_lshl_add_u64 v[178:179], s[70:71], 0, v[138:139]
	ds_read_b128 v[186:189], v163 offset:32768
	ds_read_b128 v[190:193], v163 offset:33792
	ds_read_b128 v[194:197], v163 offset:34816
	ds_read_b128 v[198:201], v163 offset:35840
	ds_read_b128 v[202:205], v163 offset:36864
	ds_read_b128 v[206:209], v163 offset:37888
	ds_read_b128 v[210:213], v163 offset:38912
	ds_read_b128 v[214:217], v163 offset:39936
	global_load_lds_dwordx4 v[178:179], off
	v_lshl_add_u64 v[178:179], s[70:71], 0, v[140:141]
	s_mov_b32 m0, s75
	s_nop 0
	global_load_lds_dwordx4 v[178:179], off
	s_waitcnt vmcnt(8)
	s_waitcnt lgkmcnt(0)
	s_barrier
	s_setprio 1
	s_waitcnt lgkmcnt(0)
	v_mfma_f32_16x16x32_bf16 v[126:129], v[130:133], v[186:189], v[126:129]
	v_mfma_f32_16x16x32_bf16 v[122:125], v[152:155], v[186:189], v[122:125]
	v_mfma_f32_16x16x32_bf16 v[110:113], v[130:133], v[194:197], v[110:113]
	v_mfma_f32_16x16x32_bf16 v[106:109], v[152:155], v[194:197], v[106:109]
	v_mfma_f32_16x16x32_bf16 v[94:97], v[130:133], v[202:205], v[94:97]
	v_mfma_f32_16x16x32_bf16 v[90:93], v[152:155], v[202:205], v[90:93]
	v_mfma_f32_16x16x32_bf16 v[78:81], v[130:133], v[210:213], v[78:81]
	v_mfma_f32_16x16x32_bf16 v[74:77], v[152:155], v[210:213], v[74:77]
	v_mfma_f32_16x16x32_bf16 v[126:129], v[134:137], v[190:193], v[126:129]
	v_mfma_f32_16x16x32_bf16 v[122:125], v[156:159], v[190:193], v[122:125]
	v_mfma_f32_16x16x32_bf16 v[110:113], v[134:137], v[198:201], v[110:113]
	v_mfma_f32_16x16x32_bf16 v[106:109], v[156:159], v[198:201], v[106:109]
	v_mfma_f32_16x16x32_bf16 v[94:97], v[134:137], v[206:209], v[94:97]
	v_mfma_f32_16x16x32_bf16 v[90:93], v[156:159], v[206:209], v[90:93]
	v_mfma_f32_16x16x32_bf16 v[78:81], v[134:137], v[214:217], v[78:81]
	v_mfma_f32_16x16x32_bf16 v[74:77], v[156:159], v[214:217], v[74:77]
	s_setprio 0
	s_setprio 1
	v_mfma_f32_16x16x32_bf16 v[118:121], v[166:169], v[186:189], v[118:121]
	v_mfma_f32_16x16x32_bf16 v[114:117], v[174:177], v[186:189], v[114:117]
	v_mfma_f32_16x16x32_bf16 v[102:105], v[166:169], v[194:197], v[102:105]
	v_mfma_f32_16x16x32_bf16 v[98:101], v[174:177], v[194:197], v[98:101]
	v_mfma_f32_16x16x32_bf16 v[86:89], v[166:169], v[202:205], v[86:89]
	v_mfma_f32_16x16x32_bf16 v[82:85], v[174:177], v[202:205], v[82:85]
	v_mfma_f32_16x16x32_bf16 v[70:73], v[166:169], v[210:213], v[70:73]
	v_mfma_f32_16x16x32_bf16 v[66:69], v[174:177], v[210:213], v[66:69]
	v_mfma_f32_16x16x32_bf16 v[118:121], v[170:173], v[190:193], v[118:121]
	v_mfma_f32_16x16x32_bf16 v[114:117], v[182:185], v[190:193], v[114:117]
	v_mfma_f32_16x16x32_bf16 v[102:105], v[170:173], v[198:201], v[102:105]
	v_mfma_f32_16x16x32_bf16 v[98:101], v[182:185], v[198:201], v[98:101]
	v_mfma_f32_16x16x32_bf16 v[86:89], v[170:173], v[206:209], v[86:89]
	v_mfma_f32_16x16x32_bf16 v[82:85], v[182:185], v[206:209], v[82:85]
	v_mfma_f32_16x16x32_bf16 v[70:73], v[170:173], v[214:217], v[70:73]
	v_mfma_f32_16x16x32_bf16 v[66:69], v[182:185], v[214:217], v[66:69]
	s_setprio 0
	s_barrier
; #define PG8_STAGE(bufoff, gbase, voff) do { _Pragma("unroll") for (int _i = 0; _i < 2; ++_i) \
;         __builtin_amdgcn_global_load_lds((const unsigned*)((const char*)(gbase) + (voff)[_i]), (PG8_LAS unsigned*)(lds + (bufoff) + ldsw + _i * 8192), 16, 0, 0); } while (0)
; #define PG8_LDA(dst, b, h) do { _Pragma("unroll") for (int m = 0; m < 4; ++m) _Pragma("unroll") for (int k = 0; k < 2; ++k) dst[m][k] = *(const PG8_LAS bf16x8*)(lds + PG8_SA(b, h) + aoff + m * 2048 + k * 1024); } while (0)
; #define PG8_MMA(ai, bj, At, Bt) do { __builtin_amdgcn_s_setprio(1); _Pragma("unroll") for (int m = 0; m < 4; ++m) _Pragma("unroll") for (int n = 0; n < 2; ++n) _Pragma("unroll") for (int k = 0; k < 2; ++k) \
;         acc[ai][bj][m][n] = __builtin_amdgcn_mfma_f32_16x16x32_bf16(Bt[n][k], At[m][k], acc[ai][bj][m][n], 0, 0, 0); __builtin_amdgcn_s_setprio(0); } while (0)
; #define PG8_WAIT_V(n) asm volatile("s_waitcnt vmcnt(" #n ")" ::: "memory")
; #define PG8_WAIT_L(n) asm volatile("s_waitcnt lgkmcnt(" #n ")" ::: "memory")
; #define PG8_BAR __builtin_amdgcn_s_barrier()
; #define PG8_SCHED __builtin_amdgcn_sched_barrier(0)
; template <class Epi, class Sched, bool ALIGN_EPI = false, bool SP2 = false, bool RS = false, bool BPRE = false>
; __device__ __forceinline__ void gemm_phase(PG8_LAS unsigned char* lds, const Gemm g, const Sched& S, const Epi& E, const float* rs_ss = nullptr, PG8_LAS float* rs_tab = nullptr) {
;     ...
;             PG8_LDA(At, 1, 1); PG8_STAGE(PG8_SB(1, 0), b3, voffB); PG8_STAGE(PG8_SB(1, 1), b3 + hstep, voffB); PG8_STAGE(PG8_SA(1, 0), a3, voffA);
;             PG8_WAIT_V(8); PG8_WAIT_L(0); PG8_BAR; PG8_MMA(1, 0, At, B0); PG8_MMA(1, 1, At, B1); PG8_BAR; PG8_SCHED;
;     ...
;         if constexpr (ALIGN_EPI) { if (wr == 0) PG8_BAR; }
	s_add_u32 s70, s60, 0x4000
	s_addc_u32 s71, s61, 0
	s_add_i32 s90, s90, s15
	v_lshl_add_u64 v[178:179], s[70:71], 0, v[138:139]
	s_mov_b32 m0, s90
	ds_read_b128 v[186:189], v163 offset:49152
	ds_read_b128 v[190:193], v163 offset:50176
	ds_read_b128 v[194:197], v163 offset:51200
	ds_read_b128 v[198:201], v163 offset:52224
	ds_read_b128 v[202:205], v163 offset:53248
	ds_read_b128 v[206:209], v163 offset:54272
	ds_read_b128 v[210:213], v163 offset:55296
	ds_read_b128 v[214:217], v163 offset:56320
	global_load_lds_dwordx4 v[178:179], off
	s_add_i32 m0, s90, 0x2000
	s_add_u32 s60, s60, 0x84000
	v_lshl_add_u64 v[178:179], s[70:71], 0, v[140:141]
	s_addc_u32 s61, s61, 0
	s_add_i32 s70, s91, s15
	global_load_lds_dwordx4 v[178:179], off
	v_lshl_add_u64 v[178:179], s[60:61], 0, v[138:139]
	s_mov_b32 m0, s70
	s_nop 0
	global_load_lds_dwordx4 v[178:179], off
	v_lshl_add_u64 v[178:179], s[60:61], 0, v[140:141]
	s_add_i32 m0, s70, 0x2000
	s_nop 0
	global_load_lds_dwordx4 v[178:179], off
	v_lshl_add_u64 v[178:179], s[58:59], 0, v[138:139]
	s_mov_b32 m0, s79
	s_nop 0
	global_load_lds_dwordx4 v[178:179], off
	v_lshl_add_u64 v[178:179], s[58:59], 0, v[140:141]
	s_mov_b32 m0, s80
	s_nop 0
	global_load_lds_dwordx4 v[178:179], off
	s_waitcnt vmcnt(8)
	s_waitcnt lgkmcnt(0)
	s_barrier
	s_setprio 1
	s_waitcnt lgkmcnt(0)
	v_mfma_f32_16x16x32_bf16 v[62:65], v[130:133], v[186:189], v[62:65]
	v_mfma_f32_16x16x32_bf16 v[58:61], v[152:155], v[186:189], v[58:61]
	v_mfma_f32_16x16x32_bf16 v[46:49], v[130:133], v[194:197], v[46:49]
	v_mfma_f32_16x16x32_bf16 v[42:45], v[152:155], v[194:197], v[42:45]
	v_mfma_f32_16x16x32_bf16 v[30:33], v[130:133], v[202:205], v[30:33]
	v_mfma_f32_16x16x32_bf16 v[26:29], v[152:155], v[202:205], v[26:29]
	v_mfma_f32_16x16x32_bf16 v[14:17], v[130:133], v[210:213], v[14:17]
	v_mfma_f32_16x16x32_bf16 v[10:13], v[152:155], v[210:213], v[10:13]
	v_mfma_f32_16x16x32_bf16 v[62:65], v[134:137], v[190:193], v[62:65]
	v_mfma_f32_16x16x32_bf16 v[58:61], v[156:159], v[190:193], v[58:61]
	v_mfma_f32_16x16x32_bf16 v[46:49], v[134:137], v[198:201], v[46:49]
	v_mfma_f32_16x16x32_bf16 v[42:45], v[156:159], v[198:201], v[42:45]
	v_mfma_f32_16x16x32_bf16 v[30:33], v[134:137], v[206:209], v[30:33]
	v_mfma_f32_16x16x32_bf16 v[26:29], v[156:159], v[206:209], v[26:29]
	v_mfma_f32_16x16x32_bf16 v[14:17], v[134:137], v[214:217], v[14:17]
	v_mfma_f32_16x16x32_bf16 v[10:13], v[156:159], v[214:217], v[10:13]
	s_setprio 0
	s_setprio 1
	v_mfma_f32_16x16x32_bf16 v[54:57], v[166:169], v[186:189], v[54:57]
	v_mfma_f32_16x16x32_bf16 v[50:53], v[174:177], v[186:189], v[50:53]
	v_mfma_f32_16x16x32_bf16 v[38:41], v[166:169], v[194:197], v[38:41]
	v_mfma_f32_16x16x32_bf16 v[34:37], v[174:177], v[194:197], v[34:37]
	v_mfma_f32_16x16x32_bf16 v[22:25], v[166:169], v[202:205], v[22:25]
	v_mfma_f32_16x16x32_bf16 v[18:21], v[174:177], v[202:205], v[18:21]
	v_mfma_f32_16x16x32_bf16 v[6:9], v[166:169], v[210:213], v[6:9]
	v_mfma_f32_16x16x32_bf16 v[2:5], v[174:177], v[210:213], v[2:5]
	v_mfma_f32_16x16x32_bf16 v[54:57], v[170:173], v[190:193], v[54:57]
	v_mfma_f32_16x16x32_bf16 v[50:53], v[182:185], v[190:193], v[50:53]
	v_mfma_f32_16x16x32_bf16 v[38:41], v[170:173], v[198:201], v[38:41]
	v_mfma_f32_16x16x32_bf16 v[34:37], v[182:185], v[198:201], v[34:37]
	v_mfma_f32_16x16x32_bf16 v[22:25], v[170:173], v[206:209], v[22:25]
	v_mfma_f32_16x16x32_bf16 v[18:21], v[182:185], v[206:209], v[18:21]
	v_mfma_f32_16x16x32_bf16 v[6:9], v[170:173], v[214:217], v[6:9]
	v_mfma_f32_16x16x32_bf16 v[2:5], v[182:185], v[214:217], v[2:5]
	s_setprio 0
	s_barrier
	s_add_i32 s89, s89, 2
	s_add_u32 s56, s56, 0x8000
	s_addc_u32 s57, s57, 0
	s_add_u32 s87, s87, 0x8000
	s_addc_u32 s88, s88, 0
	s_cmp_gt_u32 s89, 29
	s_cbranch_scc0 .LBB0_196
	s_andn2_b64 vcc, s[12:13], s[6:7]
	s_cbranch_vccz .LBB0_199
	s_barrier

; #define PG8_BAR __builtin_amdgcn_s_barrier()
; template <class Epi, class Sched, bool ALIGN_EPI = false, bool SP2 = false, bool RS = false, bool BPRE = false>
; __device__ __forceinline__ void gemm_phase(PG8_LAS unsigned char* lds, const Gemm g, const Sched& S, const Epi& E, const float* rs_ss = nullptr, PG8_LAS float* rs_tab = nullptr) {
;     ...
;         if (!has_next) break;
; #pragma unroll
;         for (int a = 0; a < 2; ++a)
; #pragma unroll
;             for (int b = 0; b < 2; ++b)
; #pragma unroll
;                 for (int m = 0; m < 4; ++m)
; #pragma unroll
;                     for (int n = 0; n < 2; ++n) acc[a][b][m][n] = (f32x4){0.f, 0.f, 0.f, 0.f};
;         cur = nxt; cA = nA; cB = nB; ++ui;
;         if constexpr (RS) rs_fill(rs_tab + (ui & 1) * 768, rs_ss, cur.pm, tid);
;         if constexpr (ALIGN_EPI) { if (wr == 1) PG8_BAR; }
.LBB0_391:
	s_andn2_b64 vcc, exec, s[6:7]
	s_mov_b64 s[4:5], -1
	s_cbranch_vccnz .LBB0_192
	s_andn2_b64 vcc, exec, s[10:11]
	s_cbranch_vccnz .LBB0_191
	s_branch .LBB0_191
